# attA tile loop hand-scheduled: K/V fragment prefetch, DMA under QK MFMAs, resident ALiBi bias, exp/pack interleaved with PV MFMAs
# speedup vs baseline: 1.2342x; 1.2342x over previous
; __device__ __forceinline__ void unit(LAS unsigned char* lds, bf16_t* P1, const bf16_t* vaT, int b, int h, int qblk, float lam, const float* subln_w, const float* khalf) {
;     ...
;     const int qrow = qblk * 128 + qs * 32 + r32;
;     const size_t rowbase = (size_t)b * SEQ;
;     bf16x8 qf[4];
;     { const bf16_t* qp = P1 + (rowbase + qrow) * LDP + C_QA + (2 * h + mi) * 64 + hi * 8;
; #pragma unroll
;       for (int ks = 0; ks < 4; ++ks) qf[ks] = *(const bf16x8*)(qp + ks * 16); }
;     const float sl2 = ex2(-(float)(h + 1)) * LOG2E;
;     const float sl2h = sl2 * (float)(4 * hi);
;     float qbound;
;     { float q2 = 0.f;
; #pragma unroll
;       for (int ks = 0; ks < 4; ++ks)
; #pragma unroll
;           for (int e = 0; e < 8; ++e) { const float v = __uint_as_float((unsigned)(unsigned short)qf[ks][e] << 16); q2 += v * v; }
;       q2 += __shfl_xor(q2, 32);
;       const float* kh = khalf + (b * 16 + 2 * h + mi) * 2;
;       qbound = sqrtf(q2 * (kh[0] + kh[1])) * 1.01f + 0.05f; }
;     volatile LAS int* dflag = (volatile LAS int*)(lds + 4 * STG);
;     f32x16 O[4];
; #pragma unroll
;     for (int d = 0; d < 4; ++d)
; #pragma unroll
;         for (int r = 0; r < 16; ++r) O[d][r] = 0.f;
;     float m = -INFINITY, l = 0.f;
;     const int NT = 2 * qblk + 2;
;     const char* kbase = (const char*)(P1 + rowbase * LDP + C_KA + h * 128);
;     const char* vbase = (const char*)(vaT + (size_t)(h * 128) * MTOK + rowbase);
;     unsigned kso0, kso1, vso0, vso1;
;     { const int rk0 = (2 * wid) * 4 + (lane >> 4), rk1 = rk0 + 4, sl = lane & 15;
;       kso0 = (unsigned)((rk0 * LDP + ((sl ^ (rk0 & 15)) * 8)) * 2); kso1 = (unsigned)((rk1 * LDP + ((sl ^ (rk1 & 15)) * 8)) * 2);
;       const int d0 = (2 * wid) * 8 + (lane >> 3), d1 = d0 + 8, sv = lane & 7;
;       vso0 = (unsigned)((d0 * MTOK + ((sv ^ ((d0 >> 1) & 7)) * 8)) * 2); vso1 = (unsigned)((d1 * MTOK + ((sv ^ ((d1 >> 1) & 7)) * 8)) * 2); }
;     ...
;     unsigned koff[4], voff[4];
; #pragma unroll
;     for (int ks = 0; ks < 4; ++ks) koff[ks] = (unsigned)(r32 * 256 + (((mi * 8 + 2 * ks + hi) ^ (r32 & 15)) * 16));
; #pragma unroll
;     for (int q = 0; q < 4; ++q) voff[q] = (unsigned)(VOFF + r32 * 128 + (((2 * q + hi) ^ ((r32 >> 1) & 7)) * 16));
;     DMA_TILE(NT - 1, 0); DMA_TILE(NT - 2, 1); if (NT > 2) DMA_TILE(NT - 3, 2);
;     int stg = 0;
;     ...
;         { float slv = sl2; asm volatile("" : "+v"(slv));
; #pragma unroll
.LBB0_397:
	s_add_i32 s2, s4, 1
	v_cvt_f32_u32_e32 v0, s2
	s_waitcnt lgkmcnt(0)
	v_add_f32_e32 v4, v13, v14
	v_add_f32_e32 v2, v2, v3
	v_mul_f32_e32 v2, v2, v4
	s_mov_b32 s2, 0xf800000
	v_mul_f32_e32 v3, 0x4f800000, v2
	v_cmp_gt_f32_e32 vcc, s2, v2
	v_exp_f32_e64 v0, -v0
	s_add_i32 s73, s71, 2
	v_cndmask_b32_e32 v2, v2, v3, vcc
	v_sqrt_f32_e32 v3, v2
	v_mul_f32_e32 v127, 0x3fb8aa3b, v0
	s_add_i32 s75, s71, 1
	v_mov_b32_e32 v14, v1
	v_add_u32_e32 v0, -1, v3
	v_fma_f32 v4, -v0, v3, v2
	v_cmp_ge_f32_e64 s[2:3], 0, v4
	v_add_u32_e32 v4, 1, v3
	v_mov_b32_e32 v15, v1
	v_cndmask_b32_e64 v0, v3, v0, s[2:3]
	v_fma_f32 v3, -v4, v3, v2
	v_cmp_lt_f32_e64 s[2:3], 0, v3
	v_mov_b32_e32 v5, v1
	v_mov_b32_e32 v6, v1
	v_cndmask_b32_e64 v0, v0, v4, s[2:3]
	v_mul_f32_e32 v3, 0x37800000, v0
	v_cndmask_b32_e32 v0, v0, v3, vcc
	v_cmp_class_f32_e32 vcc, v2, v178
	s_lshl_b32 s2, s70, 3
	v_bitop3_b32 v3, s2, v148, v144 bitop3:0x36
	v_cndmask_b32_e32 v0, v0, v2, vcc
	v_or_b32_e32 v2, s2, v144
	s_lshl_b32 s2, s77, 2
	s_add_i32 s74, s2, 0
	s_add_i32 s74, s74, 0x20000
	s_lshl_b32 s2, s77, 19
	s_add_u32 s3, s44, s81
	s_addc_u32 s44, s45, 0
	s_andn2_b32 s5, 31, s5
	s_lshl_b32 s45, s5, 8
	s_add_u32 s3, s3, s45
	s_addc_u32 s45, s44, 0
	s_add_u32 s44, s66, s3
	s_addc_u32 s45, s67, s45
	s_mul_i32 s5, s5, 0x1a0000
	v_fmamk_f32 v132, v0, 0x3f8147ae, v179
	v_or_b32_e32 v0, s2, v172
	s_add_u32 s80, s80, s5
	s_mov_b32 s5, s11
	v_lshl_add_u64 v[134:135], v[0:1], 0, s[20:21]
	v_or_b32_e32 v0, s2, v173
	s_addc_u32 s81, 0, 0
	s_lshl_b64 s[2:3], s[4:5], 8
	s_add_u32 s2, s80, s2
	v_add_u32_e32 v0, v0, v12
	s_addc_u32 s3, s81, s3
	s_mul_i32 s4, s77, 0xd000
	v_lshl_add_u64 v[136:137], v[0:1], 0, s[20:21]
	v_add_u32_e32 v0, s4, v174
	s_add_u32 s2, s48, s2
	v_lshlrev_b32_e32 v129, 4, v3
	v_bitop3_b32 v3, v2, v148, 2 bitop3:0x36
	v_add_lshl_u32 v0, v0, v10, 1
	s_addc_u32 s3, s49, s3
	s_mul_i32 s77, s77, 0x1a000
	v_lshlrev_b32_e32 v185, 4, v3
	v_bitop3_b32 v3, v2, v148, 4 bitop3:0x36
	v_bitop3_b32 v2, v2, v148, 6 bitop3:0x36
	v_lshl_add_u64 v[138:139], s[2:3], 0, v[0:1]
	v_add3_u32 v0, v175, s77, v11
	v_lshlrev_b32_e32 v186, 4, v3
	v_lshlrev_b32_e32 v187, 4, v2
	v_lshl_add_u64 v[140:141], s[2:3], 0, v[0:1]
	v_mov_b32_e32 v0, v1
	v_mov_b32_e32 v2, v1
	v_mov_b32_e32 v3, v1
	v_mov_b32_e32 v4, v1
	v_mov_b32_e32 v7, v1
	v_mov_b32_e32 v8, v1
	v_mov_b32_e32 v9, v1
	v_mov_b32_e32 v10, v1
	v_mov_b32_e32 v11, v1
	v_mov_b32_e32 v12, v1
	v_mov_b32_e32 v13, v1
	v_mov_b64_e32 v[64:65], v[14:15]
	v_mov_b64_e32 v[48:49], v[14:15]
	v_mov_b64_e32 v[32:33], v[14:15]
	v_mul_f32_e32 v130, v127, v146
	v_mov_b64_e32 v[62:63], v[12:13]
	v_mov_b64_e32 v[60:61], v[10:11]
	v_mov_b64_e32 v[58:59], v[8:9]
	v_mov_b64_e32 v[56:57], v[6:7]
	v_mov_b64_e32 v[54:55], v[4:5]
	v_mov_b64_e32 v[52:53], v[2:3]
	v_mov_b64_e32 v[50:51], v[0:1]
	v_mov_b64_e32 v[46:47], v[12:13]
	v_mov_b64_e32 v[44:45], v[10:11]
	v_mov_b64_e32 v[42:43], v[8:9]
	v_mov_b64_e32 v[40:41], v[6:7]
	v_mov_b64_e32 v[38:39], v[4:5]
	v_mov_b64_e32 v[36:37], v[2:3]
	v_mov_b64_e32 v[34:35], v[0:1]
	v_mov_b64_e32 v[30:31], v[12:13]
	v_mov_b64_e32 v[28:29], v[10:11]
	v_mov_b64_e32 v[26:27], v[8:9]
	v_mov_b64_e32 v[24:25], v[6:7]
	v_mov_b64_e32 v[22:23], v[4:5]
	v_mov_b64_e32 v[20:21], v[2:3]
	v_mov_b64_e32 v[18:19], v[0:1]
	v_mov_b64_e32 v[16:17], v[14:15]
	s_mov_b32 s10, 0
	v_mul_f32_e32 v188, 0x42000000, v127
	v_mov_b32_e32 v131, v130
	v_add_u32_e32 v189, s59, v145
	v_subrev_u32_e32 v190, s76, v177
	v_mov_b32_e32 v191, 0
	v_mov_b32_e32 v133, 0xff800000
	s_mov_b32 s76, 0
	s_mov_b32 s77, 0
	v_mov_b64_e32 v[14:15], v[12:13]
	v_mov_b64_e32 v[12:13], v[10:11]
	v_mov_b64_e32 v[10:11], v[8:9]
	v_mov_b64_e32 v[8:9], v[6:7]
	v_mov_b64_e32 v[6:7], v[4:5]
	v_mov_b64_e32 v[4:5], v[2:3]
	v_mov_b64_e32 v[2:3], v[0:1]
	s_mov_b32 s80, 0
	s_mov_b32 s81, 0
	v_mov_b32_e32 v244, v127
	v_fma_f32 v226, 0, v127, v130
	v_add_f32_e32 v227, v130, v127
	v_pk_fma_f32 v[228:229], v[244:245], s[22:23], v[130:131] op_sel_hi:[0,1,1]
	v_pk_fma_f32 v[230:231], v[244:245], s[24:25], v[130:131] op_sel_hi:[0,1,1]
	v_pk_fma_f32 v[232:233], v[244:245], s[26:27], v[130:131] op_sel_hi:[0,1,1]
	v_pk_fma_f32 v[234:235], v[244:245], s[28:29], v[130:131] op_sel_hi:[0,1,1]
	v_pk_fma_f32 v[236:237], v[244:245], s[30:31], v[130:131] op_sel_hi:[0,1,1]
	v_pk_fma_f32 v[238:239], v[244:245], s[34:35], v[130:131] op_sel_hi:[0,1,1]
	v_pk_fma_f32 v[240:241], v[244:245], s[36:37], v[130:131] op_sel_hi:[0,1,1]

; #define LAS __attribute__((address_space(3)))
; __device__ __forceinline__ int crow(int r, int hi) { return (r & 3) + 8 * (r >> 2) + 4 * hi; }
; #define MFMA32(a, b, c) __builtin_amdgcn_mfma_f32_32x32x16_bf16((a), (b), (c), 0, 0, 0)
; __device__ __forceinline__ void unit(LAS unsigned char* lds, bf16_t* P1, const bf16_t* vaT, int b, int h, int qblk, float lam, const float* subln_w, const float* khalf) {
;     ...
;     for (int jj = 0; jj < NT; ++jj) {
;         const int j = NT - 1 - jj;
;         { const bool done = __all(qbound + sl2 * (float)(64 * j + 63 - qrow) < m - 24.f);
;           if (lane == 0) dflag[(jj & 1) * 8 + wid] = done ? 1 : 0; }
;         if (jj + 2 < NT) asm volatile("s_waitcnt vmcnt(8) lgkmcnt(0)\n\ts_barrier" ::: "memory"); else if (jj + 1 < NT) asm volatile("s_waitcnt vmcnt(4) lgkmcnt(0)\n\ts_barrier" ::: "memory"); else asm volatile("s_waitcnt vmcnt(0) lgkmcnt(0)\n\ts_barrier" ::: "memory");
;         { typedef int i32x4 __attribute__((ext_vector_type(4)));
;           const i32x4 fa = *(const LAS i32x4*)(lds + 4 * STG + (jj & 1) * 32), fb = *(const LAS i32x4*)(lds + 4 * STG + (jj & 1) * 32 + 16);
;           if (((fa[0] + fa[1]) + (fa[2] + fa[3])) + ((fb[0] + fb[1]) + (fb[2] + fb[3])) == 8) break; }
;         if (jj + 3 < NT) { DMA_TILE(j - 3, (stg + 3) & 3); }
;         const LAS unsigned char* kb = lds + stg * STG;
;         stg = (stg + 1) & 3;
;         f32x16 S0, S1;
;         { float slv = sl2; asm volatile("" : "+v"(slv));
; #pragma unroll
;           for (int r = 0; r < 16; ++r) { S0[r] = __builtin_fmaf(slv, (float)((r & 3) + 8 * (r >> 2)), sl2h); S1[r] = S0[r]; } }
; #pragma unroll
;         for (int ks = 0; ks < 4; ++ks) {
;             const bf16x8 a0 = *(const LAS bf16x8*)(kb + koff[ks]);
;             const bf16x8 a1 = *(const LAS bf16x8*)(kb + koff[ks] + 32 * 256);
;             S0 = MFMA32(a0, qf[ks], S0); S1 = MFMA32(a1, qf[ks], S1);
;         }
;         const int kv0 = 64 * j;
;         if (j >= NT - 2) {
; #pragma unroll
;             for (int r = 0; r < 16; ++r) { const int kv = kv0 + crow(r, hi); if (kv > qrow) S0[r] = -INFINITY; if (kv + 32 > qrow) S1[r] = -INFINITY; }
.La_flag_done:
	s_or_b64 exec, exec, s[4:5]
	s_cmp_ge_u32 s81, s71
	s_cbranch_scc1 .La_wait_tail
	s_waitcnt vmcnt(8) lgkmcnt(0)
	s_barrier
.La_after_bar:
	s_and_b32 s2, s10, 32
	s_add_i32 s2, s2, 0x20000
	v_mov_b32_e32 v70, s2
	s_lshl_b32 s4, s80, 15
	s_add_i32 s82, s4, 0
	ds_read_b128 v[66:69], v70
	ds_read_b128 v[70:73], v70 offset:16
	v_add3_u32 v120, s82, v129, v151
	v_add3_u32 v201, s82, v185, v151
	ds_read_b128 v[192:195], v120
	ds_read_b128 v[196:199], v120 offset:8192
	v_add3_u32 v120, s82, v186, v151
	ds_read_b128 v[202:205], v201
	ds_read_b128 v[206:209], v201 offset:8192
	v_add3_u32 v201, s82, v187, v151
	ds_read_b128 v[210:213], v120
	ds_read_b128 v[214:217], v120 offset:8192
	ds_read_b128 v[218:221], v201
	ds_read_b128 v[222:225], v201 offset:8192
	s_waitcnt lgkmcnt(8)
	v_add3_u32 v66, v66, v67, v68
	v_add3_u32 v69, v69, v70, v71
	v_add_u32_e32 v72, v72, v73
	v_add3_u32 v66, v66, v69, v72
	v_cmp_eq_u32_e32 vcc, 8, v66
	s_cbranch_vccnz .LBB0_420
	s_add_i32 s5, s81, 3
	s_cmp_ge_u32 s5, s73
	s_cbranch_scc1 .La_qk_nodma
	s_add_i32 s5, s4, 0x18000
	s_and_b32 s5, s5, 0x18000
	s_add_i32 s5, s72, s5
	v_lshl_add_u64 v[252:253], s[44:45], 0, v[134:135]
	v_lshl_add_u64 v[254:255], s[44:45], 0, v[136:137]
	s_mov_b32 m0, s5
	s_waitcnt lgkmcnt(7)
	v_mfma_f32_32x32x16_bf16 v[82:97], v[192:195], v[98:101], v[226:241]
	global_load_lds_dwordx4 v[140:141], off
	s_add_i32 m0, s5, 0x400
	s_waitcnt lgkmcnt(6)
	v_mfma_f32_32x32x16_bf16 v[66:81], v[196:199], v[98:101], v[226:241]
	global_load_lds_dwordx4 v[138:139], off
	s_add_i32 m0, s5, 0x4000
	s_waitcnt lgkmcnt(5)
	v_mfma_f32_32x32x16_bf16 v[82:97], v[202:205], v[102:105], v[82:97]
	global_load_lds_dwordx4 v[252:253], off
	s_add_i32 m0, s5, 0x4400
	s_waitcnt lgkmcnt(4)
	v_mfma_f32_32x32x16_bf16 v[66:81], v[206:209], v[102:105], v[66:81]
	global_load_lds_dwordx4 v[254:255], off
	s_waitcnt lgkmcnt(3)
	v_mfma_f32_32x32x16_bf16 v[82:97], v[210:213], v[106:109], v[82:97]
	s_waitcnt lgkmcnt(2)
	v_mfma_f32_32x32x16_bf16 v[66:81], v[214:217], v[106:109], v[66:81]
	s_waitcnt lgkmcnt(1)
	v_mfma_f32_32x32x16_bf16 v[82:97], v[218:221], v[110:113], v[82:97]
	s_waitcnt lgkmcnt(0)
	v_mfma_f32_32x32x16_bf16 v[66:81], v[222:225], v[110:113], v[66:81]
	s_branch .La_qk_done
.La_qk_nodma:
	s_waitcnt lgkmcnt(7)
	v_mfma_f32_32x32x16_bf16 v[82:97], v[192:195], v[98:101], v[226:241]
	s_waitcnt lgkmcnt(6)
	v_mfma_f32_32x32x16_bf16 v[66:81], v[196:199], v[98:101], v[226:241]
	s_waitcnt lgkmcnt(5)
	v_mfma_f32_32x32x16_bf16 v[82:97], v[202:205], v[102:105], v[82:97]
	s_waitcnt lgkmcnt(4)
	v_mfma_f32_32x32x16_bf16 v[66:81], v[206:209], v[102:105], v[66:81]
	s_waitcnt lgkmcnt(3)
	v_mfma_f32_32x32x16_bf16 v[82:97], v[210:213], v[106:109], v[82:97]
	s_waitcnt lgkmcnt(2)
	v_mfma_f32_32x32x16_bf16 v[66:81], v[214:217], v[106:109], v[66:81]
	s_waitcnt lgkmcnt(1)
	v_mfma_f32_32x32x16_bf16 v[82:97], v[218:221], v[110:113], v[82:97]
	s_waitcnt lgkmcnt(0)
	v_mfma_f32_32x32x16_bf16 v[66:81], v[222:225], v[110:113], v[66:81]
.La_qk_done:
	v_add_u32_e32 v244, s82, v168
	v_add_u32_e32 v245, s82, v169
	v_add_u32_e32 v246, s82, v170
	v_add_u32_e32 v247, s82, v171
	ds_read_b128 v[192:195], v244 offset:16384
	ds_read_b128 v[196:199], v244 offset:20480
	ds_read_b128 v[202:205], v244 offset:24576
	ds_read_b128 v[206:209], v244 offset:28672
	ds_read_b128 v[210:213], v245 offset:16384
	ds_read_b128 v[214:217], v245 offset:20480
	ds_read_b128 v[218:221], v245 offset:24576
	ds_read_b128 v[222:225], v245 offset:28672
	s_cmp_lt_i32 s75, s71
	s_cbranch_scc1 .La_nomask
	v_add_u32_e32 v243, s76, v189
	v_add_u32_e32 v250, 0x60, v243
	v_add_u32_e32 v251, 64, v243
	v_cmp_le_i32_e32 vcc, v250, v125
	s_nop 6
	v_cndmask_b32_e32 v66, v184, v66, vcc
	v_cmp_lt_i32_e32 vcc, v251, v125
	s_nop 1
	v_cndmask_b32_e32 v83, v184, v83, vcc
	v_cmp_le_i32_e32 vcc, v251, v125
	v_add_u32_e32 v251, 0x61, v243
	s_nop 0
	v_cndmask_b32_e32 v82, v184, v82, vcc
	v_cmp_le_i32_e32 vcc, v251, v125
	v_add_u32_e32 v251, 0x42, v243
	s_nop 0
	v_cndmask_b32_e32 v67, v184, v67, vcc
	v_cmp_le_i32_e32 vcc, v251, v125
	v_add_u32_e32 v251, 0x62, v243
	s_nop 0
	v_cndmask_b32_e32 v84, v184, v84, vcc
	v_cmp_le_i32_e32 vcc, v251, v125
	v_add_u32_e32 v251, 0x43, v243
	s_nop 0
	v_cndmask_b32_e32 v68, v184, v68, vcc
	v_cmp_le_i32_e32 vcc, v251, v125
	v_add_u32_e32 v251, 0x63, v243
	s_nop 0
	v_cndmask_b32_e32 v85, v184, v85, vcc
	v_cmp_le_i32_e32 vcc, v251, v125
	v_add_u32_e32 v251, 0x48, v243
	s_nop 0
	v_cndmask_b32_e32 v69, v184, v69, vcc
	v_cmp_le_i32_e32 vcc, v251, v125
	v_add_u32_e32 v251, 0x68, v243
	s_nop 0
	v_cndmask_b32_e32 v86, v184, v86, vcc
	v_cmp_le_i32_e32 vcc, v251, v125
	v_add_u32_e32 v251, 0x49, v243
	s_nop 0
	v_cndmask_b32_e32 v70, v184, v70, vcc
	v_cmp_le_i32_e32 vcc, v251, v125
	v_add_u32_e32 v251, 0x69, v243
	s_nop 0
	v_cndmask_b32_e32 v87, v184, v87, vcc
	v_cmp_le_i32_e32 vcc, v251, v125
	v_add_u32_e32 v251, 0x4a, v243
	s_nop 0
	v_cndmask_b32_e32 v71, v184, v71, vcc
	v_cmp_le_i32_e32 vcc, v251, v125
	v_add_u32_e32 v251, 0x6a, v243
	s_nop 0
	v_cndmask_b32_e32 v88, v184, v88, vcc
	v_cmp_le_i32_e32 vcc, v251, v125
	v_add_u32_e32 v251, 0x4b, v243
	s_nop 0
	v_cndmask_b32_e32 v72, v184, v72, vcc
	v_cmp_le_i32_e32 vcc, v251, v125
	v_add_u32_e32 v251, 0x6b, v243
	s_nop 0
	v_cndmask_b32_e32 v89, v184, v89, vcc
	v_cmp_le_i32_e32 vcc, v251, v125
	v_add_u32_e32 v251, 0x50, v243
	s_nop 0
	v_cndmask_b32_e32 v73, v184, v73, vcc
	v_cmp_le_i32_e32 vcc, v251, v125
	v_add_u32_e32 v251, 0x70, v243
	s_nop 0
	v_cndmask_b32_e32 v90, v184, v90, vcc
	v_cmp_le_i32_e32 vcc, v251, v125
	v_add_u32_e32 v251, 0x51, v243
	s_nop 0
	v_cndmask_b32_e32 v74, v184, v74, vcc
	v_cmp_le_i32_e32 vcc, v251, v125
; __device__ __forceinline__ int crow(int r, int hi) { return (r & 3) + 8 * (r >> 2) + 4 * hi; }
; __device__ __forceinline__ float ex2(float v) { return __builtin_amdgcn_exp2f(v); }
; __device__ __forceinline__ void unit(LAS unsigned char* lds, bf16_t* P1, const bf16_t* vaT, int b, int h, int qblk, float lam, const float* subln_w, const float* khalf) {
;     ...
;             for (int r = 0; r < 16; ++r) { const int kv = kv0 + crow(r, hi); if (kv > qrow) S0[r] = -INFINITY; if (kv + 32 > qrow) S1[r] = -INFINITY; }
;         }
;         const float tb0 = sl2 * (float)(kv0 - qrow), tb1 = tb0 + sl2 * 32.f;
;         float mx0 = S0[0], mx1 = S1[0];
; #pragma unroll
;         for (int r = 1; r < 16; ++r) { mx0 = fmaxf(mx0, S0[r]); mx1 = fmaxf(mx1, S1[r]); }
;         float mt = fmaxf(mx0 + tb0, mx1 + tb1); mt = fmaxf(mt, __shfl_xor(mt, 32));
;         const bool skip = __all((mt < m - 24.f) || (mt == -INFINITY));
;         if (!skip) {
;         const float mn = fmaxf(m, mt); const float alpha = ex2(m - mn); m = mn;
;         const float c0 = tb0 - mn, c1 = tb1 - mn;
;         f32x2 ps2 = (f32x2){0.f, 0.f};
; #pragma unroll
;         for (int r = 0; r < 16; r += 2) { f32x2 a = (f32x2){S0[r], S0[r + 1]} + c0, bq = (f32x2){S1[r], S1[r + 1]} + c1;
;             a.x = ex2(a.x); a.y = ex2(a.y); bq.x = ex2(bq.x); bq.y = ex2(bq.y); S0[r] = a.x; S0[r + 1] = a.y; S1[r] = bq.x; S1[r + 1] = bq.y; ps2 = ps2 + a; ps2 = ps2 + bq; }
;         l = l * alpha + (ps2.x + ps2.y);
;         if (__any(alpha != 1.f)) {
; #pragma unroll
;             for (int d = 0; d < 4; ++d) O[d] = O[d] * alpha;
	v_add_u32_e32 v251, 0x71, v243
	s_nop 0
	v_cndmask_b32_e32 v91, v184, v91, vcc
	v_cmp_le_i32_e32 vcc, v251, v125
	v_add_u32_e32 v251, 0x52, v243
	s_nop 0
	v_cndmask_b32_e32 v75, v184, v75, vcc
	v_cmp_le_i32_e32 vcc, v251, v125
	v_add_u32_e32 v251, 0x72, v243
	s_nop 0
	v_cndmask_b32_e32 v92, v184, v92, vcc
	v_cmp_le_i32_e32 vcc, v251, v125
	v_add_u32_e32 v251, 0x53, v243
	s_nop 0
	v_cndmask_b32_e32 v76, v184, v76, vcc
	v_cmp_le_i32_e32 vcc, v251, v125
	v_add_u32_e32 v251, 0x73, v243
	s_nop 0
	v_cndmask_b32_e32 v93, v184, v93, vcc
	v_cmp_le_i32_e32 vcc, v251, v125
	v_add_u32_e32 v251, 0x58, v243
	s_nop 0
	v_cndmask_b32_e32 v77, v184, v77, vcc
	v_cmp_le_i32_e32 vcc, v251, v125
	v_add_u32_e32 v251, 0x78, v243
	s_nop 0
	v_cndmask_b32_e32 v94, v184, v94, vcc
	v_cmp_le_i32_e32 vcc, v251, v125
	v_add_u32_e32 v251, 0x59, v243
	s_nop 0
	v_cndmask_b32_e32 v78, v184, v78, vcc
	v_cmp_le_i32_e32 vcc, v251, v125
	v_add_u32_e32 v251, 0x79, v243
	s_nop 0
	v_cndmask_b32_e32 v95, v184, v95, vcc
	v_cmp_le_i32_e32 vcc, v251, v125
	v_add_u32_e32 v251, 0x5a, v243
	s_nop 0
	v_cndmask_b32_e32 v79, v184, v79, vcc
	v_cmp_le_i32_e32 vcc, v251, v125
	v_add_u32_e32 v251, 0x7a, v243
	s_nop 0
	v_cndmask_b32_e32 v96, v184, v96, vcc
	v_cmp_le_i32_e32 vcc, v251, v125
	v_add_u32_e32 v251, 0x5b, v243
	v_add_u32_e32 v243, 0x7b, v243
	v_cndmask_b32_e32 v80, v184, v80, vcc
	v_cmp_le_i32_e32 vcc, v251, v125
	s_nop 1
	v_cndmask_b32_e32 v97, v184, v97, vcc
	v_cmp_le_i32_e32 vcc, v243, v125
	s_nop 1
	v_cndmask_b32_e32 v81, v184, v81, vcc
.La_nomask:
	v_add_u32_e32 v0, 64, v0
	v_cvt_f32_i32_e32 v142, v0
	v_max3_f32 v0, v82, v83, v84
	v_max3_f32 v120, v66, v67, v68
	v_max3_f32 v0, v0, v85, v86
	v_max3_f32 v120, v120, v69, v70
	v_max3_f32 v0, v0, v87, v88
	v_max3_f32 v120, v120, v71, v72
	v_max3_f32 v0, v0, v89, v90
	v_max3_f32 v120, v120, v73, v74
	v_max3_f32 v0, v0, v91, v92
	v_max3_f32 v120, v120, v75, v76
	v_max3_f32 v0, v0, v93, v94
	v_max3_f32 v120, v120, v77, v78
	v_max3_f32 v0, v0, v95, v96
	v_max3_f32 v120, v120, v79, v80
	v_max_f32_e32 v0, v0, v97
	v_max_f32_e32 v120, v120, v81
	v_fma_f32 v248, v127, v142, v188
	v_fmac_f32_e32 v0, v127, v142
	v_add_f32_e32 v120, v248, v120
	v_max_f32_e32 v0, v0, v120
	ds_bpermute_b32 v120, v115, v0
	s_waitcnt lgkmcnt(0)
	v_max_f32_e32 v0, v0, v120
	v_cmp_lt_f32_e32 vcc, v0, v143
	v_cmp_eq_f32_e64 s[4:5], v0, v184
	s_or_b64 s[4:5], vcc, s[4:5]
	s_cmp_eq_u64 s[4:5], exec
	s_cbranch_scc1 .La_latch
	v_max_f32_e32 v120, v133, v0
	v_sub_f32_e32 v0, v133, v120
	v_exp_f32_e32 v0, v0
	v_mul_f32_e32 v142, v127, v142
	v_sub_f32_e32 v142, v142, v120
	v_sub_f32_e32 v248, v248, v120
	v_mov_b32_e32 v133, v120
	v_cmp_neq_f32_e32 vcc, 1.0, v0
	s_cbranch_vccz .La_norescale
	v_pk_mul_f32 v[64:65], v[64:65], v[0:1] op_sel_hi:[1,0]
	v_pk_mul_f32 v[62:63], v[62:63], v[0:1] op_sel_hi:[1,0]
	v_pk_mul_f32 v[60:61], v[60:61], v[0:1] op_sel_hi:[1,0]
	v_pk_mul_f32 v[58:59], v[58:59], v[0:1] op_sel_hi:[1,0]
	v_pk_mul_f32 v[56:57], v[56:57], v[0:1] op_sel_hi:[1,0]
	v_pk_mul_f32 v[54:55], v[54:55], v[0:1] op_sel_hi:[1,0]
	v_pk_mul_f32 v[52:53], v[52:53], v[0:1] op_sel_hi:[1,0]
	v_pk_mul_f32 v[50:51], v[50:51], v[0:1] op_sel_hi:[1,0]
	v_pk_mul_f32 v[48:49], v[48:49], v[0:1] op_sel_hi:[1,0]
	v_pk_mul_f32 v[46:47], v[46:47], v[0:1] op_sel_hi:[1,0]
	v_pk_mul_f32 v[44:45], v[44:45], v[0:1] op_sel_hi:[1,0]
	v_pk_mul_f32 v[42:43], v[42:43], v[0:1] op_sel_hi:[1,0]
	v_pk_mul_f32 v[40:41], v[40:41], v[0:1] op_sel_hi:[1,0]
	v_pk_mul_f32 v[38:39], v[38:39], v[0:1] op_sel_hi:[1,0]
	v_pk_mul_f32 v[36:37], v[36:37], v[0:1] op_sel_hi:[1,0]
	v_pk_mul_f32 v[34:35], v[34:35], v[0:1] op_sel_hi:[1,0]
	v_pk_mul_f32 v[32:33], v[32:33], v[0:1] op_sel_hi:[1,0]
	v_pk_mul_f32 v[30:31], v[30:31], v[0:1] op_sel_hi:[1,0]
	v_pk_mul_f32 v[28:29], v[28:29], v[0:1] op_sel_hi:[1,0]
	v_pk_mul_f32 v[26:27], v[26:27], v[0:1] op_sel_hi:[1,0]
	v_pk_mul_f32 v[24:25], v[24:25], v[0:1] op_sel_hi:[1,0]
	v_pk_mul_f32 v[22:23], v[22:23], v[0:1] op_sel_hi:[1,0]
	v_pk_mul_f32 v[20:21], v[20:21], v[0:1] op_sel_hi:[1,0]
	v_pk_mul_f32 v[18:19], v[18:19], v[0:1] op_sel_hi:[1,0]
	v_pk_mul_f32 v[16:17], v[16:17], v[0:1] op_sel_hi:[1,0]
	v_pk_mul_f32 v[14:15], v[14:15], v[0:1] op_sel_hi:[1,0]
	v_pk_mul_f32 v[12:13], v[12:13], v[0:1] op_sel_hi:[1,0]
	v_pk_mul_f32 v[10:11], v[10:11], v[0:1] op_sel_hi:[1,0]
	v_pk_mul_f32 v[8:9], v[8:9], v[0:1] op_sel_hi:[1,0]
	v_pk_mul_f32 v[6:7], v[6:7], v[0:1] op_sel_hi:[1,0]
	v_pk_mul_f32 v[4:5], v[4:5], v[0:1] op_sel_hi:[1,0]
	v_pk_mul_f32 v[2:3], v[2:3], v[0:1] op_sel_hi:[1,0]
; #define LAS __attribute__((address_space(3)))
; __device__ __forceinline__ unsigned cvtpk(float lo, float hi) { return pg8::cvt_pk_bf16(lo, hi); }
; __device__ __forceinline__ void unit(LAS unsigned char* lds, bf16_t* P1, const bf16_t* vaT, int b, int h, int qblk, float lam, const float* subln_w, const float* khalf) {
;     ...
;     for (int jj = 0; jj < NT; ++jj) {
;         const int j = NT - 1 - jj;
;         { const bool done = __all(qbound + sl2 * (float)(64 * j + 63 - qrow) < m - 24.f);
;           if (lane == 0) dflag[(jj & 1) * 8 + wid] = done ? 1 : 0; }
;         if (jj + 2 < NT) asm volatile("s_waitcnt vmcnt(8) lgkmcnt(0)\n\ts_barrier" ::: "memory"); else if (jj + 1 < NT) asm volatile("s_waitcnt vmcnt(4) lgkmcnt(0)\n\ts_barrier" ::: "memory"); else asm volatile("s_waitcnt vmcnt(0) lgkmcnt(0)\n\ts_barrier" ::: "memory");
;     ...
;         if (!skip) {
;         const float mn = fmaxf(m, mt); const float alpha = ex2(m - mn); m = mn;
;         const float c0 = tb0 - mn, c1 = tb1 - mn;
;         f32x2 ps2 = (f32x2){0.f, 0.f};
; #pragma unroll
;         for (int r = 0; r < 16; r += 2) { f32x2 a = (f32x2){S0[r], S0[r + 1]} + c0, bq = (f32x2){S1[r], S1[r + 1]} + c1;
;             a.x = ex2(a.x); a.y = ex2(a.y); bq.x = ex2(bq.x); bq.y = ex2(bq.y); S0[r] = a.x; S0[r + 1] = a.y; S1[r] = bq.x; S1[r + 1] = bq.y; ps2 = ps2 + a; ps2 = ps2 + bq; }
;         l = l * alpha + (ps2.x + ps2.y);
;         if (__any(alpha != 1.f)) {
; #pragma unroll
;             for (int d = 0; d < 4; ++d) O[d] = O[d] * alpha;
;         }
;         u32x4 pk[2][2];
; #pragma unroll
;         for (int s = 0; s < 2; ++s) {
;             pk[0][s] = (u32x4){cvtpk(S0[8 * s + 0], S0[8 * s + 1]), cvtpk(S0[8 * s + 2], S0[8 * s + 3]), cvtpk(S0[8 * s + 4], S0[8 * s + 5]), cvtpk(S0[8 * s + 6], S0[8 * s + 7])};
;             pk[1][s] = (u32x4){cvtpk(S1[8 * s + 0], S1[8 * s + 1]), cvtpk(S1[8 * s + 2], S1[8 * s + 3]), cvtpk(S1[8 * s + 4], S1[8 * s + 5]), cvtpk(S1[8 * s + 6], S1[8 * s + 7])};
;         }
; #pragma unroll
;         for (int d = 0; d < 4; ++d)
; #pragma unroll
;             for (int t2 = 0; t2 < 2; ++t2)
; #pragma unroll
;                 for (int s = 0; s < 2; ++s) {
;                     const bf16x8 vf = *(const LAS bf16x8*)(kb + voff[2 * t2 + s] + d * 32 * 128);
;                     O[d] = MFMA32(vf, __builtin_bit_cast(bf16x8, pk[t2][s]), O[d]);
;                 }
;         }
.La_norescale:
	v_pk_add_f32 v[82:83], v[82:83], v[142:143] op_sel_hi:[1,0]
	v_pk_add_f32 v[84:85], v[84:85], v[142:143] op_sel_hi:[1,0]
	v_pk_add_f32 v[86:87], v[86:87], v[142:143] op_sel_hi:[1,0]
	v_pk_add_f32 v[88:89], v[88:89], v[142:143] op_sel_hi:[1,0]
	v_exp_f32_e32 v82, v82
	v_exp_f32_e32 v83, v83
	v_exp_f32_e32 v84, v84
	v_exp_f32_e32 v85, v85
	v_exp_f32_e32 v86, v86
	v_exp_f32_e32 v87, v87
	v_exp_f32_e32 v88, v88
	v_exp_f32_e32 v89, v89
	v_mov_b32_e32 v250, v82
	v_add_f32_e32 v250, v250, v83
	v_add_f32_e32 v250, v250, v84
	v_add_f32_e32 v250, v250, v85
	v_cvt_pk_bf16_f32 v82, v82, v83
	v_cvt_pk_bf16_f32 v83, v84, v85
	v_cvt_pk_bf16_f32 v84, v86, v87
	v_cvt_pk_bf16_f32 v85, v88, v89
	v_add_f32_e32 v250, v250, v86
	v_add_f32_e32 v250, v250, v87
	v_add_f32_e32 v250, v250, v88
	v_add_f32_e32 v250, v250, v89
	v_mfma_f32_32x32x16_bf16 v[50:65], v[192:195], v[82:85], v[50:65]
	ds_read_b128 v[192:195], v246 offset:16384
	v_pk_add_f32 v[90:91], v[90:91], v[142:143] op_sel_hi:[1,0]
	v_pk_add_f32 v[92:93], v[92:93], v[142:143] op_sel_hi:[1,0]
	v_pk_add_f32 v[94:95], v[94:95], v[142:143] op_sel_hi:[1,0]
	v_pk_add_f32 v[96:97], v[96:97], v[142:143] op_sel_hi:[1,0]
	v_exp_f32_e32 v90, v90
	v_exp_f32_e32 v91, v91
	v_mfma_f32_32x32x16_bf16 v[34:49], v[196:199], v[82:85], v[34:49]
	ds_read_b128 v[196:199], v246 offset:20480
	v_exp_f32_e32 v92, v92
	v_exp_f32_e32 v93, v93
	v_exp_f32_e32 v94, v94
	v_exp_f32_e32 v95, v95
	v_exp_f32_e32 v96, v96
	v_exp_f32_e32 v97, v97
	v_mfma_f32_32x32x16_bf16 v[18:33], v[202:205], v[82:85], v[18:33]
	ds_read_b128 v[202:205], v246 offset:24576
	v_add_f32_e32 v250, v250, v90
	v_add_f32_e32 v250, v250, v91
	v_add_f32_e32 v250, v250, v92
	v_add_f32_e32 v250, v250, v93
	v_cvt_pk_bf16_f32 v90, v90, v91
	v_cvt_pk_bf16_f32 v91, v92, v93
	v_mfma_f32_32x32x16_bf16 v[2:17], v[206:209], v[82:85], v[2:17]
	ds_read_b128 v[206:209], v246 offset:28672
	v_cvt_pk_bf16_f32 v92, v94, v95
	v_cvt_pk_bf16_f32 v93, v96, v97
	v_add_f32_e32 v250, v250, v94
	v_add_f32_e32 v250, v250, v95
	v_add_f32_e32 v250, v250, v96
	v_add_f32_e32 v250, v250, v97
	v_mfma_f32_32x32x16_bf16 v[50:65], v[210:213], v[90:93], v[50:65]
	ds_read_b128 v[210:213], v247 offset:16384
	v_pk_add_f32 v[66:67], v[66:67], v[248:249] op_sel_hi:[1,0]
	v_pk_add_f32 v[68:69], v[68:69], v[248:249] op_sel_hi:[1,0]
	v_pk_add_f32 v[70:71], v[70:71], v[248:249] op_sel_hi:[1,0]
	v_pk_add_f32 v[72:73], v[72:73], v[248:249] op_sel_hi:[1,0]
	v_exp_f32_e32 v66, v66
	v_exp_f32_e32 v67, v67
	v_mfma_f32_32x32x16_bf16 v[34:49], v[214:217], v[90:93], v[34:49]
	ds_read_b128 v[214:217], v247 offset:20480
	v_exp_f32_e32 v68, v68
	v_exp_f32_e32 v69, v69
	v_exp_f32_e32 v70, v70
	v_exp_f32_e32 v71, v71
	v_exp_f32_e32 v72, v72
	v_exp_f32_e32 v73, v73
	v_mfma_f32_32x32x16_bf16 v[18:33], v[218:221], v[90:93], v[18:33]
	ds_read_b128 v[218:221], v247 offset:24576
	v_mov_b32_e32 v251, v66
	v_add_f32_e32 v251, v251, v67
	v_add_f32_e32 v251, v251, v68
	v_add_f32_e32 v251, v251, v69
	v_cvt_pk_bf16_f32 v66, v66, v67
	v_cvt_pk_bf16_f32 v67, v68, v69
	v_mfma_f32_32x32x16_bf16 v[2:17], v[222:225], v[90:93], v[2:17]
	ds_read_b128 v[222:225], v247 offset:28672
	v_cvt_pk_bf16_f32 v68, v70, v71
	v_cvt_pk_bf16_f32 v69, v72, v73
	v_add_f32_e32 v251, v251, v70
	v_add_f32_e32 v251, v251, v71
	v_add_f32_e32 v251, v251, v72
	v_add_f32_e32 v251, v251, v73
	s_waitcnt lgkmcnt(7)
	v_mfma_f32_32x32x16_bf16 v[50:65], v[192:195], v[66:69], v[50:65]
	v_pk_add_f32 v[74:75], v[74:75], v[248:249] op_sel_hi:[1,0]
	v_pk_add_f32 v[76:77], v[76:77], v[248:249] op_sel_hi:[1,0]
	v_pk_add_f32 v[78:79], v[78:79], v[248:249] op_sel_hi:[1,0]
	v_pk_add_f32 v[80:81], v[80:81], v[248:249] op_sel_hi:[1,0]
	v_exp_f32_e32 v74, v74
	v_exp_f32_e32 v75, v75
	s_waitcnt lgkmcnt(6)
	v_mfma_f32_32x32x16_bf16 v[34:49], v[196:199], v[66:69], v[34:49]
	v_exp_f32_e32 v76, v76
	v_exp_f32_e32 v77, v77
	v_exp_f32_e32 v78, v78
	v_exp_f32_e32 v79, v79
	v_exp_f32_e32 v80, v80
	v_exp_f32_e32 v81, v81
	s_waitcnt lgkmcnt(5)
	v_mfma_f32_32x32x16_bf16 v[18:33], v[202:205], v[66:69], v[18:33]
	v_add_f32_e32 v251, v251, v74
	v_add_f32_e32 v251, v251, v75
	v_add_f32_e32 v251, v251, v76
	v_add_f32_e32 v251, v251, v77
	v_cvt_pk_bf16_f32 v74, v74, v75
	v_cvt_pk_bf16_f32 v75, v76, v77
	s_waitcnt lgkmcnt(4)
	v_mfma_f32_32x32x16_bf16 v[2:17], v[206:209], v[66:69], v[2:17]
	v_cvt_pk_bf16_f32 v76, v78, v79
	v_cvt_pk_bf16_f32 v77, v80, v81
	v_add_f32_e32 v251, v251, v78
	v_add_f32_e32 v251, v251, v79
	v_add_f32_e32 v251, v251, v80
	v_add_f32_e32 v251, v251, v81
	s_waitcnt lgkmcnt(3)
	v_mfma_f32_32x32x16_bf16 v[50:65], v[210:213], v[74:77], v[50:65]
	v_add_f32_e32 v250, v250, v251
	s_waitcnt lgkmcnt(2)
	v_mfma_f32_32x32x16_bf16 v[34:49], v[214:217], v[74:77], v[34:49]
	v_fma_f32 v191, v191, v0, v250
	s_waitcnt lgkmcnt(1)
	v_mfma_f32_32x32x16_bf16 v[18:33], v[218:221], v[74:77], v[18:33]
	s_waitcnt lgkmcnt(0)
	v_mfma_f32_32x32x16_bf16 v[2:17], v[222:225], v[74:77], v[2:17]
.La_latch:
	s_add_i32 s80, s80, 1
	s_and_b32 s80, s80, 3
	s_add_i32 s4, s59, s76
	s_add_i32 s81, s81, 1
	s_add_i32 s77, s77, 8
	s_add_i32 s10, s10, 32
	s_add_i32 s75, s75, -1
	s_sub_i32 s76, s76, 64
	s_add_u32 s44, s44, 0xffffff80
	s_addc_u32 s45, s45, -1
	v_lshl_add_u64 v[138:139], v[138:139], 0, s[38:39]
	v_lshl_add_u64 v[140:141], v[140:141], 0, s[38:39]
	s_cmpk_eq_i32 s4, 0xffc0
	s_cbranch_scc0 .La_top
	s_branch .LBB0_420
.La_wait_tail:
	s_cmp_gt_u32 s81, s71
	s_cbranch_scc1 .La_wait_last
	s_waitcnt vmcnt(4) lgkmcnt(0)
	s_barrier
	s_branch .La_after_bar
.La_wait_last:
	s_waitcnt vmcnt(0) lgkmcnt(0)
	s_barrier
	s_branch .La_after_bar

; __global__ void __launch_bounds__(NTHR, 2) fwd_kernel(Ptrs P) {
	.amdhsa_kernel _Z10fwd_kernel4Ptrs
		.amdhsa_group_segment_fixed_size 0
		.amdhsa_private_segment_fixed_size 0
		.amdhsa_kernarg_size 432
		.amdhsa_user_sgpr_count 2
		.amdhsa_user_sgpr_dispatch_ptr 0
		.amdhsa_user_sgpr_queue_ptr 0
		.amdhsa_user_sgpr_kernarg_segment_ptr 1
		.amdhsa_user_sgpr_dispatch_id 0
		.amdhsa_user_sgpr_kernarg_preload_length 0
		.amdhsa_user_sgpr_kernarg_preload_offset 0
		.amdhsa_user_sgpr_private_segment_size 0
		.amdhsa_uses_dynamic_stack 0
		.amdhsa_enable_private_segment 0
		.amdhsa_system_sgpr_workgroup_id_x 1
		.amdhsa_system_sgpr_workgroup_id_y 0
		.amdhsa_system_sgpr_workgroup_id_z 0
		.amdhsa_system_sgpr_workgroup_info 0
		.amdhsa_system_vgpr_workitem_id 2
		.amdhsa_next_free_vgpr 256
		.amdhsa_next_free_sgpr 98
		.amdhsa_accum_offset 256
		.amdhsa_reserve_vcc 1
		.amdhsa_float_round_mode_32 0
		.amdhsa_float_round_mode_16_64 0
		.amdhsa_float_denorm_mode_32 3
		.amdhsa_float_denorm_mode_16_64 3
		.amdhsa_dx10_clamp 1
		.amdhsa_ieee_mode 1
		.amdhsa_fp16_overflow 0
		.amdhsa_tg_split 0
		.amdhsa_exception_fp_ieee_invalid_op 0
		.amdhsa_exception_fp_denorm_src 0
		.amdhsa_exception_fp_ieee_div_zero 0
		.amdhsa_exception_fp_ieee_overflow 0
		.amdhsa_exception_fp_ieee_underflow 0
		.amdhsa_exception_fp_ieee_inexact 0
		.amdhsa_exception_int_div_zero 0
	.end_amdhsa_kernel

; __global__ void __launch_bounds__(NTHR, 2) fwd_kernel(Ptrs P) {
amdhsa.kernels:
  - .agpr_count:     0
    .args:
      - .offset:         0
        .size:           176
        .value_kind:     by_value
      - .offset:         176
        .size:           4
        .value_kind:     hidden_block_count_x
      - .offset:         180
        .size:           4
        .value_kind:     hidden_block_count_y
      - .offset:         184
        .size:           4
        .value_kind:     hidden_block_count_z
      - .offset:         188
        .size:           2
        .value_kind:     hidden_group_size_x
      - .offset:         190
        .size:           2
        .value_kind:     hidden_group_size_y
      - .offset:         192
        .size:           2
        .value_kind:     hidden_group_size_z
      - .offset:         194
        .size:           2
        .value_kind:     hidden_remainder_x
      - .offset:         196
        .size:           2
        .value_kind:     hidden_remainder_y
      - .offset:         198
        .size:           2
        .value_kind:     hidden_remainder_z
      - .offset:         216
        .size:           8
        .value_kind:     hidden_global_offset_x
      - .offset:         224
        .size:           8
        .value_kind:     hidden_global_offset_y
      - .offset:         232
        .size:           8
        .value_kind:     hidden_global_offset_z
      - .offset:         240
        .size:           2
        .value_kind:     hidden_grid_dims
      - .offset:         264
        .size:           8
        .value_kind:     hidden_multigrid_sync_arg
      - .offset:         296
        .size:           4
        .value_kind:     hidden_dynamic_lds_size
    .group_segment_fixed_size: 0
    .kernarg_segment_align: 8
    .kernarg_segment_size: 432
    .language:       OpenCL C
    .language_version:
      - 2
      - 0
    .max_flat_workgroup_size: 512
    .name:           _Z10fwd_kernel4Ptrs
    .private_segment_fixed_size: 0
    .sgpr_count:     104
    .sgpr_spill_count: 53
    .symbol:         _Z10fwd_kernel4Ptrs.kd
    .uniform_work_group_size: 1
    .uses_dynamic_stack: false
    .vgpr_count:     256
    .vgpr_spill_count: 0
    .wavefront_size: 64
